# out-proj / FFN-down epilogues: row-contiguous thread mapping for the residual loads and output stores (each wave instruction covers two full 512-byte rows)
# speedup vs baseline: 1.0881x; 1.0235x over previous
; template <int MODE, bool BIG = false> DI void gemm_tile(const Params& p, int tm, int tn, int kv, char* smem) {
;     ...
;   const int row = tid >> 1, half = tid & 1;
;   float* crow = Cs + row * 132 + half * 64;
;   const float4* crow4 = (const float4*)crow;
;   const int m = tm * RB + hh * 128 + row;
;   const int col0 = tn * 128 + half * 64;
;     ...
;   } else if constexpr (MODE == G_OUT) {
;     const float4* x4 = (const float4*)(p.x + (size_t)m * 1024 + col0);
;     float4* o4 = (float4*)(p.out + (size_t)m * 1024 + col0);
; #pragma unroll
;     for (int c4 = 0; c4 < 16; ++c4) { float4 v = crow4[c4], xx = x4[c4]; o4[c4] = make_float4(v.x + xx.x, v.y + xx.y, v.z + xx.z, v.w + xx.w); }
.LBB0_940:
	s_or_b64 exec, exec, s[6:7]
	v_lshl_add_u32 v136, s14, 7, v134
	v_ashrrev_i32_e32 v137, 31, v136
	v_lshlrev_b64 v[148:149], 12, v[136:137]
	v_lshl_add_u64 v[150:151], v[128:129], 0, v[148:149]
	v_lshrrev_b32_e32 v136, 5, v173
	v_lshrrev_b32_e32 v139, 1, v173
	v_sub_u32_e32 v138, v136, v139
	v_lshlrev_b32_e32 v138, 12, v138
	v_and_b32_e32 v139, 1, v173
	v_lshlrev_b32_e32 v139, 8, v139
	v_sub_u32_e32 v138, v138, v139
	v_and_b32_e32 v139, 31, v173
	v_lshl_add_u32 v138, v139, 4, v138
	v_mul_u32_u24_e32 v136, 0x210, v136
	v_lshl_add_u32 v136, v139, 4, v136
	v_ashrrev_i32_e32 v139, 31, v138
	v_lshl_add_u64 v[150:151], v[150:151], 0, v[138:139]
	v_mov_b32_e32 v152, 0x8000
	global_load_dwordx4 v[184:187], v[150:151], off
	v_lshl_add_u64 v[150:151], v[152:153], 0, v[150:151]
	global_load_dwordx4 v[192:195], v[150:151], off
	v_lshl_add_u64 v[150:151], v[152:153], 0, v[150:151]
	global_load_dwordx4 v[200:203], v[150:151], off
	v_lshl_add_u64 v[150:151], v[152:153], 0, v[150:151]
	global_load_dwordx4 v[208:211], v[150:151], off
	v_lshl_add_u64 v[150:151], v[152:153], 0, v[150:151]
	global_load_dwordx4 v[216:219], v[150:151], off
	v_lshl_add_u64 v[150:151], v[152:153], 0, v[150:151]
	global_load_dwordx4 v[224:227], v[150:151], off
	v_lshl_add_u64 v[150:151], v[152:153], 0, v[150:151]
	global_load_dwordx4 v[188:191], v[150:151], off
	v_lshl_add_u64 v[150:151], v[152:153], 0, v[150:151]
	global_load_dwordx4 v[196:199], v[150:151], off
	v_lshl_add_u64 v[150:151], v[152:153], 0, v[150:151]
	global_load_dwordx4 v[204:207], v[150:151], off
	v_lshl_add_u64 v[150:151], v[152:153], 0, v[150:151]
	global_load_dwordx4 v[212:215], v[150:151], off
	v_lshl_add_u64 v[150:151], v[152:153], 0, v[150:151]
	global_load_dwordx4 v[220:223], v[150:151], off
	v_lshl_add_u64 v[150:151], v[152:153], 0, v[150:151]
	global_load_dwordx4 v[228:231], v[150:151], off
	v_lshl_add_u64 v[150:151], v[152:153], 0, v[150:151]
	s_waitcnt lgkmcnt(0)
	s_barrier
	v_lshl_add_u64 v[148:149], v[130:131], 0, v[148:149]
	s_xor_b64 s[2:3], s[2:3], -1
	s_mov_b32 s14, 1
	s_andn2_b64 vcc, exec, s[2:3]
	s_mov_b64 s[2:3], 0
	v_lshl_add_u64 v[148:149], v[148:149], 0, v[138:139]
	ds_read_b128 v[140:143], v136
	ds_read_b128 v[144:147], v136 offset:4224
	s_waitcnt vmcnt(11) lgkmcnt(1)
	v_pk_add_f32 v[184:185], v[140:141], v[184:185]
	v_pk_add_f32 v[186:187], v[142:143], v[186:187]
	global_store_dwordx4 v[148:149], v[184:187], off
	v_lshl_add_u64 v[148:149], v[152:153], 0, v[148:149]
	s_waitcnt vmcnt(11) lgkmcnt(0)
	v_pk_add_f32 v[192:193], v[144:145], v[192:193]
	v_pk_add_f32 v[194:195], v[146:147], v[194:195]
	global_store_dwordx4 v[148:149], v[192:195], off
	v_lshl_add_u64 v[148:149], v[152:153], 0, v[148:149]
	global_load_dwordx4 v[184:187], v[150:151], off
	v_lshl_add_u64 v[150:151], v[152:153], 0, v[150:151]
	ds_read_b128 v[140:143], v136 offset:8448
	ds_read_b128 v[144:147], v136 offset:12672
	s_waitcnt vmcnt(12) lgkmcnt(1)
	v_pk_add_f32 v[200:201], v[140:141], v[200:201]
	v_pk_add_f32 v[202:203], v[142:143], v[202:203]
	global_store_dwordx4 v[148:149], v[200:203], off
	v_lshl_add_u64 v[148:149], v[152:153], 0, v[148:149]
	global_load_dwordx4 v[192:195], v[150:151], off
	v_lshl_add_u64 v[150:151], v[152:153], 0, v[150:151]
	s_waitcnt vmcnt(13) lgkmcnt(0)
	v_pk_add_f32 v[208:209], v[144:145], v[208:209]
	v_pk_add_f32 v[210:211], v[146:147], v[210:211]
	global_store_dwordx4 v[148:149], v[208:211], off
	v_lshl_add_u64 v[148:149], v[152:153], 0, v[148:149]
	global_load_dwordx4 v[200:203], v[150:151], off
	v_lshl_add_u64 v[150:151], v[152:153], 0, v[150:151]
	ds_read_b128 v[140:143], v136 offset:16896
	ds_read_b128 v[144:147], v136 offset:21120
	s_waitcnt vmcnt(14) lgkmcnt(1)
	v_pk_add_f32 v[216:217], v[140:141], v[216:217]
	v_pk_add_f32 v[218:219], v[142:143], v[218:219]
	global_store_dwordx4 v[148:149], v[216:219], off
	v_lshl_add_u64 v[148:149], v[152:153], 0, v[148:149]
	global_load_dwordx4 v[208:211], v[150:151], off
	v_lshl_add_u64 v[150:151], v[152:153], 0, v[150:151]
	s_waitcnt vmcnt(15) lgkmcnt(0)
	v_pk_add_f32 v[224:225], v[144:145], v[224:225]
	v_pk_add_f32 v[226:227], v[146:147], v[226:227]
	global_store_dwordx4 v[148:149], v[224:227], off
	v_lshl_add_u64 v[148:149], v[152:153], 0, v[148:149]
	ds_read_b128 v[140:143], v136 offset:25344
	ds_read_b128 v[144:147], v136 offset:29568
	s_waitcnt vmcnt(15) lgkmcnt(1)
	v_pk_add_f32 v[188:189], v[140:141], v[188:189]
	v_pk_add_f32 v[190:191], v[142:143], v[190:191]
	global_store_dwordx4 v[148:149], v[188:191], off
	v_lshl_add_u64 v[148:149], v[152:153], 0, v[148:149]
	s_waitcnt vmcnt(15) lgkmcnt(0)
	v_pk_add_f32 v[196:197], v[144:145], v[196:197]
	v_pk_add_f32 v[198:199], v[146:147], v[198:199]
	global_store_dwordx4 v[148:149], v[196:199], off
	v_lshl_add_u64 v[148:149], v[152:153], 0, v[148:149]
	ds_read_b128 v[140:143], v136 offset:33792
	ds_read_b128 v[144:147], v136 offset:38016
	s_waitcnt vmcnt(15) lgkmcnt(1)
	v_pk_add_f32 v[204:205], v[140:141], v[204:205]
	v_pk_add_f32 v[206:207], v[142:143], v[206:207]
	global_store_dwordx4 v[148:149], v[204:207], off
	v_lshl_add_u64 v[148:149], v[152:153], 0, v[148:149]
	s_waitcnt vmcnt(15) lgkmcnt(0)
	v_pk_add_f32 v[212:213], v[144:145], v[212:213]
	v_pk_add_f32 v[214:215], v[146:147], v[214:215]
	global_store_dwordx4 v[148:149], v[212:215], off
	v_lshl_add_u64 v[148:149], v[152:153], 0, v[148:149]
	ds_read_b128 v[140:143], v136 offset:42240
	ds_read_b128 v[144:147], v136 offset:46464
	s_waitcnt vmcnt(15) lgkmcnt(1)
	v_pk_add_f32 v[220:221], v[140:141], v[220:221]
	v_pk_add_f32 v[222:223], v[142:143], v[222:223]
	global_store_dwordx4 v[148:149], v[220:223], off
	v_lshl_add_u64 v[148:149], v[152:153], 0, v[148:149]
	s_waitcnt vmcnt(15) lgkmcnt(0)
	v_pk_add_f32 v[228:229], v[144:145], v[228:229]
	v_pk_add_f32 v[230:231], v[146:147], v[230:231]
	global_store_dwordx4 v[148:149], v[228:231], off
	v_lshl_add_u64 v[148:149], v[152:153], 0, v[148:149]
	ds_read_b128 v[140:143], v136 offset:50688
	ds_read_b128 v[144:147], v136 offset:54912
	s_waitcnt vmcnt(13) lgkmcnt(1)
	v_pk_add_f32 v[184:185], v[140:141], v[184:185]
	v_pk_add_f32 v[186:187], v[142:143], v[186:187]
	global_store_dwordx4 v[148:149], v[184:187], off
	v_lshl_add_u64 v[148:149], v[152:153], 0, v[148:149]
	s_waitcnt vmcnt(12) lgkmcnt(0)
	v_pk_add_f32 v[192:193], v[144:145], v[192:193]
	v_pk_add_f32 v[194:195], v[146:147], v[194:195]
	global_store_dwordx4 v[148:149], v[192:195], off
	v_lshl_add_u64 v[148:149], v[152:153], 0, v[148:149]
	ds_read_b128 v[140:143], v136 offset:59136
	ds_read_b128 v[144:147], v136 offset:63360
	s_waitcnt vmcnt(11) lgkmcnt(1)
	v_pk_add_f32 v[200:201], v[140:141], v[200:201]
	v_pk_add_f32 v[202:203], v[142:143], v[202:203]
	global_store_dwordx4 v[148:149], v[200:203], off
	v_lshl_add_u64 v[148:149], v[152:153], 0, v[148:149]
	s_waitcnt vmcnt(10) lgkmcnt(0)
	v_pk_add_f32 v[208:209], v[144:145], v[208:209]
	v_pk_add_f32 v[210:211], v[146:147], v[210:211]
	global_store_dwordx4 v[148:149], v[208:211], off
	v_lshl_add_u64 v[148:149], v[152:153], 0, v[148:149]
	s_cbranch_vccz .LBB0_936

; template <int MODE, bool BIG = false> DI void gemm_tile(const Params& p, int tm, int tn, int kv, char* smem) {
;     ...
;   const int row = tid >> 1, half = tid & 1;
;   float* crow = Cs + row * 132 + half * 64;
;   const float4* crow4 = (const float4*)crow;
;   const int m = tm * RB + hh * 128 + row;
;   const int col0 = tn * 128 + half * 64;
;     ...
;   } else if constexpr (MODE == G_FF2) {
;     float4* o4 = (float4*)(p.out + (size_t)m * 1024 + col0);
; #pragma unroll
;     for (int c4 = 0; c4 < 16; ++c4) { float4 v = crow4[c4], xx = o4[c4]; o4[c4] = make_float4(v.x + xx.x, v.y + xx.y, v.z + xx.z, v.w + xx.w); }
.LBB0_1003:
	s_or_b64 exec, exec, s[4:5]
	v_lshl_add_u32 v130, s14, 7, v134
	v_ashrrev_i32_e32 v131, 31, v130
	v_lshlrev_b64 v[130:131], 12, v[130:131]
	v_lshl_add_u64 v[130:131], v[128:129], 0, v[130:131]
	v_lshrrev_b32_e32 v144, 5, v173
	v_lshrrev_b32_e32 v147, 1, v173
	v_sub_u32_e32 v146, v144, v147
	v_lshlrev_b32_e32 v146, 12, v146
	v_and_b32_e32 v147, 1, v173
	v_lshlrev_b32_e32 v147, 8, v147
	v_sub_u32_e32 v146, v146, v147
	v_and_b32_e32 v147, 31, v173
	v_lshl_add_u32 v146, v147, 4, v146
	v_mul_u32_u24_e32 v144, 0x210, v144
	v_lshl_add_u32 v144, v147, 4, v144
	v_ashrrev_i32_e32 v147, 31, v146
	v_lshl_add_u64 v[130:131], v[130:131], 0, v[146:147]
	v_mov_b64_e32 v[146:147], v[130:131]
	v_mov_b32_e32 v152, 0x8000
	global_load_dwordx4 v[188:191], v[130:131], off
	v_lshl_add_u64 v[130:131], v[152:153], 0, v[130:131]
	global_load_dwordx4 v[196:199], v[130:131], off
	v_lshl_add_u64 v[130:131], v[152:153], 0, v[130:131]
	global_load_dwordx4 v[204:207], v[130:131], off
	v_lshl_add_u64 v[130:131], v[152:153], 0, v[130:131]
	global_load_dwordx4 v[212:215], v[130:131], off
	v_lshl_add_u64 v[130:131], v[152:153], 0, v[130:131]
	global_load_dwordx4 v[220:223], v[130:131], off
	v_lshl_add_u64 v[130:131], v[152:153], 0, v[130:131]
	global_load_dwordx4 v[228:231], v[130:131], off
	v_lshl_add_u64 v[130:131], v[152:153], 0, v[130:131]
	global_load_dwordx4 v[192:195], v[130:131], off
	v_lshl_add_u64 v[130:131], v[152:153], 0, v[130:131]
	global_load_dwordx4 v[200:203], v[130:131], off
	v_lshl_add_u64 v[130:131], v[152:153], 0, v[130:131]
	global_load_dwordx4 v[208:211], v[130:131], off
	v_lshl_add_u64 v[130:131], v[152:153], 0, v[130:131]
	global_load_dwordx4 v[216:219], v[130:131], off
	v_lshl_add_u64 v[130:131], v[152:153], 0, v[130:131]
	global_load_dwordx4 v[224:227], v[130:131], off
	v_lshl_add_u64 v[130:131], v[152:153], 0, v[130:131]
	global_load_dwordx4 v[232:235], v[130:131], off
	v_lshl_add_u64 v[130:131], v[152:153], 0, v[130:131]
	global_load_dwordx4 v[148:151], v[130:131], off
	v_lshl_add_u64 v[130:131], v[152:153], 0, v[130:131]
	s_waitcnt lgkmcnt(0)
	s_barrier
	s_xor_b64 s[4:5], s[6:7], -1
	s_mov_b32 s14, 1
	s_mov_b64 s[6:7], 0
	s_andn2_b64 vcc, exec, s[4:5]
	ds_read_b128 v[136:139], v144
	ds_read_b128 v[140:143], v144 offset:4224
	s_waitcnt vmcnt(12) lgkmcnt(1)
	v_pk_add_f32 v[188:189], v[136:137], v[188:189]
	v_pk_add_f32 v[190:191], v[138:139], v[190:191]
	global_store_dwordx4 v[146:147], v[188:191], off
	v_lshl_add_u64 v[146:147], v[152:153], 0, v[146:147]
	s_waitcnt vmcnt(12) lgkmcnt(0)
	v_pk_add_f32 v[196:197], v[140:141], v[196:197]
	v_pk_add_f32 v[198:199], v[142:143], v[198:199]
	global_store_dwordx4 v[146:147], v[196:199], off
	v_lshl_add_u64 v[146:147], v[152:153], 0, v[146:147]
	global_load_dwordx4 v[188:191], v[130:131], off
	v_lshl_add_u64 v[130:131], v[152:153], 0, v[130:131]
	ds_read_b128 v[136:139], v144 offset:8448
	ds_read_b128 v[140:143], v144 offset:12672
	s_waitcnt vmcnt(13) lgkmcnt(1)
	v_pk_add_f32 v[204:205], v[136:137], v[204:205]
	v_pk_add_f32 v[206:207], v[138:139], v[206:207]
	global_store_dwordx4 v[146:147], v[204:207], off
	v_lshl_add_u64 v[146:147], v[152:153], 0, v[146:147]
	global_load_dwordx4 v[196:199], v[130:131], off
	v_lshl_add_u64 v[130:131], v[152:153], 0, v[130:131]
	s_waitcnt vmcnt(14) lgkmcnt(0)
	v_pk_add_f32 v[212:213], v[140:141], v[212:213]
	v_pk_add_f32 v[214:215], v[142:143], v[214:215]
	global_store_dwordx4 v[146:147], v[212:215], off
	v_lshl_add_u64 v[146:147], v[152:153], 0, v[146:147]
	global_load_dwordx4 v[204:207], v[130:131], off
	v_lshl_add_u64 v[130:131], v[152:153], 0, v[130:131]
	ds_read_b128 v[136:139], v144 offset:16896
	ds_read_b128 v[140:143], v144 offset:21120
	s_waitcnt vmcnt(15) lgkmcnt(1)
	v_pk_add_f32 v[220:221], v[136:137], v[220:221]
	v_pk_add_f32 v[222:223], v[138:139], v[222:223]
	global_store_dwordx4 v[146:147], v[220:223], off
	v_lshl_add_u64 v[146:147], v[152:153], 0, v[146:147]
	s_waitcnt vmcnt(15) lgkmcnt(0)
	v_pk_add_f32 v[228:229], v[140:141], v[228:229]
	v_pk_add_f32 v[230:231], v[142:143], v[230:231]
	global_store_dwordx4 v[146:147], v[228:231], off
	v_lshl_add_u64 v[146:147], v[152:153], 0, v[146:147]
	ds_read_b128 v[136:139], v144 offset:25344
	ds_read_b128 v[140:143], v144 offset:29568
	s_waitcnt vmcnt(15) lgkmcnt(1)
	v_pk_add_f32 v[192:193], v[136:137], v[192:193]
	v_pk_add_f32 v[194:195], v[138:139], v[194:195]
	global_store_dwordx4 v[146:147], v[192:195], off
	v_lshl_add_u64 v[146:147], v[152:153], 0, v[146:147]
	s_waitcnt vmcnt(15) lgkmcnt(0)
	v_pk_add_f32 v[200:201], v[140:141], v[200:201]
	v_pk_add_f32 v[202:203], v[142:143], v[202:203]
	global_store_dwordx4 v[146:147], v[200:203], off
	v_lshl_add_u64 v[146:147], v[152:153], 0, v[146:147]
	ds_read_b128 v[136:139], v144 offset:33792
	ds_read_b128 v[140:143], v144 offset:38016
	s_waitcnt vmcnt(15) lgkmcnt(1)
	v_pk_add_f32 v[208:209], v[136:137], v[208:209]
	v_pk_add_f32 v[210:211], v[138:139], v[210:211]
	global_store_dwordx4 v[146:147], v[208:211], off
	v_lshl_add_u64 v[146:147], v[152:153], 0, v[146:147]
	s_waitcnt vmcnt(15) lgkmcnt(0)
	v_pk_add_f32 v[216:217], v[140:141], v[216:217]
	v_pk_add_f32 v[218:219], v[142:143], v[218:219]
	global_store_dwordx4 v[146:147], v[216:219], off
	v_lshl_add_u64 v[146:147], v[152:153], 0, v[146:147]
	ds_read_b128 v[136:139], v144 offset:42240
	ds_read_b128 v[140:143], v144 offset:46464
	s_waitcnt vmcnt(15) lgkmcnt(1)
	v_pk_add_f32 v[224:225], v[136:137], v[224:225]
	v_pk_add_f32 v[226:227], v[138:139], v[226:227]
	global_store_dwordx4 v[146:147], v[224:227], off
	v_lshl_add_u64 v[146:147], v[152:153], 0, v[146:147]
	s_waitcnt vmcnt(15) lgkmcnt(0)
	v_pk_add_f32 v[232:233], v[140:141], v[232:233]
	v_pk_add_f32 v[234:235], v[142:143], v[234:235]
	global_store_dwordx4 v[146:147], v[232:235], off
	v_lshl_add_u64 v[146:147], v[152:153], 0, v[146:147]
	ds_read_b128 v[136:139], v144 offset:50688
	ds_read_b128 v[140:143], v144 offset:54912
	s_waitcnt vmcnt(15) lgkmcnt(1)
	v_pk_add_f32 v[148:149], v[136:137], v[148:149]
	v_pk_add_f32 v[150:151], v[138:139], v[150:151]
	global_store_dwordx4 v[146:147], v[148:151], off
	v_lshl_add_u64 v[146:147], v[152:153], 0, v[146:147]
	s_waitcnt vmcnt(13) lgkmcnt(0)
	v_pk_add_f32 v[188:189], v[140:141], v[188:189]
	v_pk_add_f32 v[190:191], v[142:143], v[190:191]
	global_store_dwordx4 v[146:147], v[188:191], off
	v_lshl_add_u64 v[146:147], v[152:153], 0, v[146:147]
	ds_read_b128 v[136:139], v144 offset:59136
	ds_read_b128 v[140:143], v144 offset:63360
	s_waitcnt vmcnt(12) lgkmcnt(1)
	v_pk_add_f32 v[196:197], v[136:137], v[196:197]
	v_pk_add_f32 v[198:199], v[138:139], v[198:199]
	global_store_dwordx4 v[146:147], v[196:199], off
	v_lshl_add_u64 v[146:147], v[152:153], 0, v[146:147]
	s_waitcnt vmcnt(11) lgkmcnt(0)
	v_pk_add_f32 v[204:205], v[140:141], v[204:205]
	v_pk_add_f32 v[206:207], v[142:143], v[206:207]
	global_store_dwordx4 v[146:147], v[204:207], off
	v_lshl_add_u64 v[146:147], v[152:153], 0, v[146:147]
	s_cbranch_vccz .LBB0_999
